# q8_strip32 load phase software-pipelined: 16 loads in flight per wave instead of 8 (ping-pong register sets + copies)
# baseline (speedup 1.0000x reference)
.LBB0_103:
	s_ashr_i32 s1, s0, 31
	s_lshl_b64 s[2:3], s[0:1], 2
	s_add_u32 s2, s14, s2
	s_addc_u32 s3, s15, s3
	s_add_u32 s8, s2, 0x8000
	s_addc_u32 s2, s3, 0
	s_and_b32 s9, s2, 0xffff
	s_mov_b32 s2, 0x10000
	buffer_load_dwordx4 v[208:211], v13, s[8:11], 0 offen nt
	buffer_load_dwordx4 v[212:215], v13, s[8:11], s11 offen nt
	buffer_load_dwordx4 v[216:219], v13, s[8:11], s2 offen nt
	s_mov_b32 s2, 0x30000
	buffer_load_dwordx4 v[220:223], v13, s[8:11], s2 offen nt
	s_mov_b32 s2, 0x40000
	buffer_load_dwordx4 v[224:227], v13, s[8:11], s2 offen nt
	s_mov_b32 s2, 0x50000
	buffer_load_dwordx4 v[228:231], v13, s[8:11], s2 offen nt
	s_mov_b32 s2, 0x60000
	buffer_load_dwordx4 v[232:235], v13, s[8:11], s2 offen nt
	s_mov_b32 s2, 0x70000
	buffer_load_dwordx4 v[236:239], v13, s[8:11], s2 offen nt
	s_mov_b32 s2, 0x80000
	buffer_load_dwordx4 v[164:167], v13, s[8:11], s2 offen nt
	s_mov_b32 s2, 0x90000
	buffer_load_dwordx4 v[168:171], v13, s[8:11], s2 offen nt
	s_mov_b32 s2, 0xa0000
	buffer_load_dwordx4 v[172:175], v13, s[8:11], s2 offen nt
	s_mov_b32 s2, 0xb0000
	buffer_load_dwordx4 v[176:179], v13, s[8:11], s2 offen nt
	s_mov_b32 s2, 0xc0000
	buffer_load_dwordx4 v[180:183], v13, s[8:11], s2 offen nt
	s_mov_b32 s2, 0xd0000
	buffer_load_dwordx4 v[184:187], v13, s[8:11], s2 offen nt
	s_mov_b32 s2, 0xe0000
	buffer_load_dwordx4 v[188:191], v13, s[8:11], s2 offen nt
	s_mov_b32 s2, 0xf0000
	buffer_load_dwordx4 v[192:195], v13, s[8:11], s2 offen nt
	s_waitcnt vmcnt(8)
	v_mov_b32_e32 v6, v208
	v_mov_b32_e32 v7, v209
	v_mov_b32_e32 v8, v210
	v_mov_b32_e32 v9, v211
	v_mov_b32_e32 v24, v212
	v_mov_b32_e32 v25, v213
	v_mov_b32_e32 v26, v214
	v_mov_b32_e32 v27, v215
	v_mov_b32_e32 v28, v216
	v_mov_b32_e32 v29, v217
	v_mov_b32_e32 v30, v218
	v_mov_b32_e32 v31, v219
	v_mov_b32_e32 v32, v220
	v_mov_b32_e32 v33, v221
	v_mov_b32_e32 v34, v222
	v_mov_b32_e32 v35, v223
	v_mov_b32_e32 v36, v224
	v_mov_b32_e32 v37, v225
	v_mov_b32_e32 v38, v226
	v_mov_b32_e32 v39, v227
	v_mov_b32_e32 v40, v228
	v_mov_b32_e32 v41, v229
	v_mov_b32_e32 v42, v230
	v_mov_b32_e32 v43, v231
	v_mov_b32_e32 v44, v232
	v_mov_b32_e32 v45, v233
	v_mov_b32_e32 v46, v234
	v_mov_b32_e32 v47, v235
	v_mov_b32_e32 v48, v236
	v_mov_b32_e32 v49, v237
	v_mov_b32_e32 v50, v238
	v_mov_b32_e32 v51, v239
	s_mov_b32 s2, 0x100000
	buffer_load_dwordx4 v[208:211], v13, s[8:11], s2 offen nt
	s_mov_b32 s2, 0x110000
	buffer_load_dwordx4 v[212:215], v13, s[8:11], s2 offen nt
	s_mov_b32 s2, 0x120000
	buffer_load_dwordx4 v[216:219], v13, s[8:11], s2 offen nt
	s_mov_b32 s2, 0x130000
	buffer_load_dwordx4 v[220:223], v13, s[8:11], s2 offen nt
	s_mov_b32 s2, 0x140000
	buffer_load_dwordx4 v[224:227], v13, s[8:11], s2 offen nt
	s_mov_b32 s2, 0x150000
	buffer_load_dwordx4 v[228:231], v13, s[8:11], s2 offen nt
	s_mov_b32 s2, 0x160000
	buffer_load_dwordx4 v[232:235], v13, s[8:11], s2 offen nt
	s_mov_b32 s2, 0x170000
	buffer_load_dwordx4 v[236:239], v13, s[8:11], s2 offen nt
	v_max3_f32 v10, |v6|, 0, |v28|
	v_max3_f32 v11, |v7|, 0, |v29|
	v_max3_f32 v12, |v8|, 0, |v30|
	v_max3_f32 v14, |v9|, 0, |v31|
	v_max3_f32 v10, v10, |v24|, |v32|
	v_max3_f32 v11, v11, |v25|, |v33|
	v_max3_f32 v12, v12, |v26|, |v34|
	v_max3_f32 v14, v14, |v27|, |v35|
	v_max3_f32 v10, v10, |v36|, |v40|
	v_max3_f32 v11, v11, |v37|, |v41|
	v_max3_f32 v12, v12, |v38|, |v42|
	v_max3_f32 v14, v14, |v39|, |v43|
	v_cvt_pk_bf16_f32 v52, v6, v28
	v_cvt_pk_bf16_f32 v53, v24, v32
	v_cvt_pk_bf16_f32 v54, v36, v40
	v_cvt_pk_bf16_f32 v55, v44, v48
	v_max3_f32 v10, v10, |v44|, |v48|
	v_max3_f32 v11, v11, |v45|, |v49|
	v_max3_f32 v12, v12, |v46|, |v50|
	v_max3_f32 v14, v14, |v47|, |v51|
	ds_write_b128 v16, v[52:55]
	v_cvt_pk_bf16_f32 v52, v7, v29
	v_cvt_pk_bf16_f32 v53, v25, v33
	v_cvt_pk_bf16_f32 v54, v37, v41
	v_cvt_pk_bf16_f32 v55, v45, v49
	ds_write_b128 v16, v[52:55] offset:1024
	v_cvt_pk_bf16_f32 v52, v8, v30
	v_cvt_pk_bf16_f32 v53, v26, v34
	v_cvt_pk_bf16_f32 v54, v38, v42
	v_cvt_pk_bf16_f32 v55, v46, v50
	ds_write_b128 v16, v[52:55] offset:2048
	v_cvt_pk_bf16_f32 v6, v9, v31
	v_cvt_pk_bf16_f32 v7, v27, v35
	v_cvt_pk_bf16_f32 v8, v39, v43
	v_cvt_pk_bf16_f32 v9, v47, v51
	ds_write_b128 v16, v[6:9] offset:3072
	s_waitcnt vmcnt(8)
	v_mov_b32_e32 v6, v164
	v_mov_b32_e32 v7, v165
	v_mov_b32_e32 v8, v166
	v_mov_b32_e32 v9, v167
	v_mov_b32_e32 v24, v168
	v_mov_b32_e32 v25, v169
	v_mov_b32_e32 v26, v170
	v_mov_b32_e32 v27, v171
	v_mov_b32_e32 v28, v172
	v_mov_b32_e32 v29, v173
	v_mov_b32_e32 v30, v174
	v_mov_b32_e32 v31, v175
	v_mov_b32_e32 v32, v176
	v_mov_b32_e32 v33, v177
	v_mov_b32_e32 v34, v178
	v_mov_b32_e32 v35, v179
	v_mov_b32_e32 v36, v180
	v_mov_b32_e32 v37, v181
	v_mov_b32_e32 v38, v182
	v_mov_b32_e32 v39, v183
	v_mov_b32_e32 v40, v184
	v_mov_b32_e32 v41, v185
	v_mov_b32_e32 v42, v186
	v_mov_b32_e32 v43, v187
	v_mov_b32_e32 v44, v188
	v_mov_b32_e32 v45, v189
	v_mov_b32_e32 v46, v190
	v_mov_b32_e32 v47, v191
	v_mov_b32_e32 v48, v192
	v_mov_b32_e32 v49, v193
	v_mov_b32_e32 v50, v194
	v_mov_b32_e32 v51, v195
	s_mov_b32 s2, 0x180000
	buffer_load_dwordx4 v[164:167], v13, s[8:11], s2 offen nt
	s_mov_b32 s2, 0x190000
	buffer_load_dwordx4 v[168:171], v13, s[8:11], s2 offen nt
	s_mov_b32 s2, 0x1a0000
	buffer_load_dwordx4 v[172:175], v13, s[8:11], s2 offen nt
	s_mov_b32 s2, 0x1b0000
	buffer_load_dwordx4 v[176:179], v13, s[8:11], s2 offen nt
	s_mov_b32 s2, 0x1c0000
	buffer_load_dwordx4 v[180:183], v13, s[8:11], s2 offen nt
	s_mov_b32 s2, 0x1d0000
	buffer_load_dwordx4 v[184:187], v13, s[8:11], s2 offen nt
	s_mov_b32 s2, 0x1e0000
	buffer_load_dwordx4 v[188:191], v13, s[8:11], s2 offen nt
	s_mov_b32 s2, 0x1f0000
	buffer_load_dwordx4 v[192:195], v13, s[8:11], s2 offen nt
	v_max3_f32 v10, v10, |v6|, |v24|
	v_max3_f32 v11, v11, |v7|, |v25|
	v_max3_f32 v12, v12, |v8|, |v26|
	v_max3_f32 v14, v14, |v9|, |v27|
	v_max3_f32 v10, v10, |v28|, |v32|
	v_max3_f32 v11, v11, |v29|, |v33|
	v_max3_f32 v12, v12, |v30|, |v34|
	v_max3_f32 v14, v14, |v31|, |v35|
	v_max3_f32 v10, v10, |v36|, |v40|
	v_max3_f32 v11, v11, |v37|, |v41|
	v_max3_f32 v12, v12, |v38|, |v42|
	v_max3_f32 v14, v14, |v39|, |v43|
	v_cvt_pk_bf16_f32 v52, v6, v24
	v_cvt_pk_bf16_f32 v53, v28, v32
	v_cvt_pk_bf16_f32 v54, v36, v40
	v_cvt_pk_bf16_f32 v55, v44, v48
	v_max3_f32 v10, v10, |v44|, |v48|
	v_max3_f32 v11, v11, |v45|, |v49|
	v_max3_f32 v12, v12, |v46|, |v50|
	v_max3_f32 v14, v14, |v47|, |v51|
	ds_write_b128 v16, v[52:55] offset:4096
	v_cvt_pk_bf16_f32 v52, v7, v25
	v_cvt_pk_bf16_f32 v53, v29, v33
	v_cvt_pk_bf16_f32 v54, v37, v41
	v_cvt_pk_bf16_f32 v55, v45, v49
	ds_write_b128 v16, v[52:55] offset:5120
	v_cvt_pk_bf16_f32 v52, v8, v26
	v_cvt_pk_bf16_f32 v53, v30, v34
	v_cvt_pk_bf16_f32 v54, v38, v42
	v_cvt_pk_bf16_f32 v55, v46, v50
	ds_write_b128 v16, v[52:55] offset:6144
	v_cvt_pk_bf16_f32 v6, v9, v27
	v_cvt_pk_bf16_f32 v7, v31, v35
	v_cvt_pk_bf16_f32 v8, v39, v43
	v_cvt_pk_bf16_f32 v9, v47, v51
	ds_write_b128 v16, v[6:9] offset:7168
	s_waitcnt vmcnt(8)
	v_mov_b32_e32 v6, v208
	v_mov_b32_e32 v7, v209
	v_mov_b32_e32 v8, v210
	v_mov_b32_e32 v9, v211
	v_mov_b32_e32 v24, v212
	v_mov_b32_e32 v25, v213
	v_mov_b32_e32 v26, v214
	v_mov_b32_e32 v27, v215
	v_mov_b32_e32 v28, v216
	v_mov_b32_e32 v29, v217
	v_mov_b32_e32 v30, v218
	v_mov_b32_e32 v31, v219
	v_mov_b32_e32 v32, v220
	v_mov_b32_e32 v33, v221
	v_mov_b32_e32 v34, v222
	v_mov_b32_e32 v35, v223
	v_mov_b32_e32 v36, v224
	v_mov_b32_e32 v37, v225
	v_mov_b32_e32 v38, v226
	v_mov_b32_e32 v39, v227
	v_mov_b32_e32 v40, v228
	v_mov_b32_e32 v41, v229
	v_mov_b32_e32 v42, v230
	v_mov_b32_e32 v43, v231
	v_mov_b32_e32 v44, v232
	v_mov_b32_e32 v45, v233
	v_mov_b32_e32 v46, v234
	v_mov_b32_e32 v47, v235
	v_mov_b32_e32 v48, v236
	v_mov_b32_e32 v49, v237
	v_mov_b32_e32 v50, v238
	v_mov_b32_e32 v51, v239
	buffer_load_dwordx4 v[208:211], v13, s[8:11], s17 offen nt
	buffer_load_dwordx4 v[212:215], v13, s[8:11], s18 offen nt
	buffer_load_dwordx4 v[216:219], v13, s[8:11], s19 offen nt
	buffer_load_dwordx4 v[220:223], v13, s[8:11], s20 offen nt
	buffer_load_dwordx4 v[224:227], v13, s[8:11], s21 offen nt
	buffer_load_dwordx4 v[228:231], v13, s[8:11], s22 offen nt
	buffer_load_dwordx4 v[232:235], v13, s[8:11], s23 offen nt
	buffer_load_dwordx4 v[236:239], v13, s[8:11], s26 offen nt
	v_max3_f32 v10, v10, |v6|, |v24|
	v_max3_f32 v11, v11, |v7|, |v25|
	v_max3_f32 v12, v12, |v8|, |v26|
	v_max3_f32 v14, v14, |v9|, |v27|
	v_max3_f32 v10, v10, |v28|, |v32|
	v_max3_f32 v11, v11, |v29|, |v33|
	v_max3_f32 v12, v12, |v30|, |v34|
	v_max3_f32 v14, v14, |v31|, |v35|
	v_max3_f32 v10, v10, |v36|, |v40|
	v_max3_f32 v11, v11, |v37|, |v41|
	v_max3_f32 v12, v12, |v38|, |v42|
	v_max3_f32 v14, v14, |v39|, |v43|
	v_cvt_pk_bf16_f32 v52, v6, v24
	v_cvt_pk_bf16_f32 v53, v28, v32
	v_cvt_pk_bf16_f32 v54, v36, v40
	v_cvt_pk_bf16_f32 v55, v44, v48
	v_max3_f32 v10, v10, |v44|, |v48|
	v_max3_f32 v11, v11, |v45|, |v49|
	v_max3_f32 v12, v12, |v46|, |v50|
	v_max3_f32 v14, v14, |v47|, |v51|
	ds_write_b128 v16, v[52:55] offset:8192
	v_cvt_pk_bf16_f32 v52, v7, v25
	v_cvt_pk_bf16_f32 v53, v29, v33
	v_cvt_pk_bf16_f32 v54, v37, v41
	v_cvt_pk_bf16_f32 v55, v45, v49
	ds_write_b128 v16, v[52:55] offset:9216
	v_cvt_pk_bf16_f32 v52, v8, v26
	v_cvt_pk_bf16_f32 v53, v30, v34
	v_cvt_pk_bf16_f32 v54, v38, v42
	v_cvt_pk_bf16_f32 v55, v46, v50
	ds_write_b128 v16, v[52:55] offset:10240
	v_cvt_pk_bf16_f32 v6, v9, v27
	v_cvt_pk_bf16_f32 v7, v31, v35
	v_cvt_pk_bf16_f32 v8, v39, v43
	v_cvt_pk_bf16_f32 v9, v47, v51
	ds_write_b128 v16, v[6:9] offset:11264
	s_waitcnt vmcnt(8)
	v_mov_b32_e32 v6, v164
	v_mov_b32_e32 v7, v165
	v_mov_b32_e32 v8, v166
	v_mov_b32_e32 v9, v167
	v_mov_b32_e32 v24, v168
	v_mov_b32_e32 v25, v169
	v_mov_b32_e32 v26, v170
	v_mov_b32_e32 v27, v171
	v_mov_b32_e32 v28, v172
	v_mov_b32_e32 v29, v173
	v_mov_b32_e32 v30, v174
	v_mov_b32_e32 v31, v175
	v_mov_b32_e32 v32, v176
	v_mov_b32_e32 v33, v177
	v_mov_b32_e32 v34, v178
	v_mov_b32_e32 v35, v179
	v_mov_b32_e32 v36, v180
	v_mov_b32_e32 v37, v181
	v_mov_b32_e32 v38, v182
	v_mov_b32_e32 v39, v183
	v_mov_b32_e32 v40, v184
	v_mov_b32_e32 v41, v185
	v_mov_b32_e32 v42, v186
	v_mov_b32_e32 v43, v187
	v_mov_b32_e32 v44, v188
	v_mov_b32_e32 v45, v189
	v_mov_b32_e32 v46, v190
	v_mov_b32_e32 v47, v191
	v_mov_b32_e32 v48, v192
	v_mov_b32_e32 v49, v193
	v_mov_b32_e32 v50, v194
	v_mov_b32_e32 v51, v195
	buffer_load_dwordx4 v[164:167], v13, s[8:11], s27 offen nt
	buffer_load_dwordx4 v[168:171], v13, s[8:11], s28 offen nt
	buffer_load_dwordx4 v[172:175], v13, s[8:11], s29 offen nt
	buffer_load_dwordx4 v[176:179], v13, s[8:11], s30 offen nt
	buffer_load_dwordx4 v[180:183], v13, s[8:11], s31 offen nt
	buffer_load_dwordx4 v[184:187], v13, s[8:11], s33 offen nt
	buffer_load_dwordx4 v[188:191], v13, s[8:11], s34 offen nt
	buffer_load_dwordx4 v[192:195], v13, s[8:11], s35 offen nt
	v_max3_f32 v10, v10, |v6|, |v24|
	v_max3_f32 v11, v11, |v7|, |v25|
	v_max3_f32 v12, v12, |v8|, |v26|
	v_max3_f32 v14, v14, |v9|, |v27|
	v_max3_f32 v10, v10, |v28|, |v32|
	v_max3_f32 v11, v11, |v29|, |v33|
	v_max3_f32 v12, v12, |v30|, |v34|
	v_max3_f32 v14, v14, |v31|, |v35|
	v_max3_f32 v10, v10, |v36|, |v40|
	v_max3_f32 v11, v11, |v37|, |v41|
	v_max3_f32 v12, v12, |v38|, |v42|
	v_max3_f32 v14, v14, |v39|, |v43|
	v_cvt_pk_bf16_f32 v52, v6, v24
	v_cvt_pk_bf16_f32 v53, v28, v32
	v_cvt_pk_bf16_f32 v54, v36, v40
	v_cvt_pk_bf16_f32 v55, v44, v48
	v_max3_f32 v10, v10, |v44|, |v48|
	v_max3_f32 v11, v11, |v45|, |v49|
	v_max3_f32 v12, v12, |v46|, |v50|
	v_max3_f32 v14, v14, |v47|, |v51|
	ds_write_b128 v16, v[52:55] offset:12288
	v_cvt_pk_bf16_f32 v52, v7, v25
	v_cvt_pk_bf16_f32 v53, v29, v33
	v_cvt_pk_bf16_f32 v54, v37, v41
	v_cvt_pk_bf16_f32 v55, v45, v49
	ds_write_b128 v16, v[52:55] offset:13312
	v_cvt_pk_bf16_f32 v52, v8, v26
	v_cvt_pk_bf16_f32 v53, v30, v34
	v_cvt_pk_bf16_f32 v54, v38, v42
	v_cvt_pk_bf16_f32 v55, v46, v50
	ds_write_b128 v16, v[52:55] offset:14336
	v_cvt_pk_bf16_f32 v6, v9, v27
	v_cvt_pk_bf16_f32 v7, v31, v35
	v_cvt_pk_bf16_f32 v8, v39, v43
	v_cvt_pk_bf16_f32 v9, v47, v51
	ds_write_b128 v16, v[6:9] offset:15360
	s_waitcnt vmcnt(8)
	v_mov_b32_e32 v6, v208
	v_mov_b32_e32 v7, v209
	v_mov_b32_e32 v8, v210
	v_mov_b32_e32 v9, v211
	v_mov_b32_e32 v24, v212
	v_mov_b32_e32 v25, v213
	v_mov_b32_e32 v26, v214
	v_mov_b32_e32 v27, v215
	v_mov_b32_e32 v28, v216
	v_mov_b32_e32 v29, v217
	v_mov_b32_e32 v30, v218
	v_mov_b32_e32 v31, v219
	v_mov_b32_e32 v32, v220
	v_mov_b32_e32 v33, v221
	v_mov_b32_e32 v34, v222
	v_mov_b32_e32 v35, v223
	v_mov_b32_e32 v36, v224
	v_mov_b32_e32 v37, v225
	v_mov_b32_e32 v38, v226
	v_mov_b32_e32 v39, v227
	v_mov_b32_e32 v42, v228
	v_mov_b32_e32 v43, v229
	v_mov_b32_e32 v44, v230
	v_mov_b32_e32 v45, v231
	v_mov_b32_e32 v46, v232
	v_mov_b32_e32 v47, v233
	v_mov_b32_e32 v48, v234
	v_mov_b32_e32 v49, v235
	v_mov_b32_e32 v50, v236
	v_mov_b32_e32 v51, v237
	v_mov_b32_e32 v52, v238
	v_mov_b32_e32 v53, v239
	buffer_load_dwordx4 v[208:211], v13, s[8:11], s36 offen nt
	buffer_load_dwordx4 v[212:215], v13, s[8:11], s37 offen nt
	buffer_load_dwordx4 v[216:219], v13, s[8:11], s38 offen nt
	buffer_load_dwordx4 v[220:223], v13, s[8:11], s39 offen nt
	buffer_load_dwordx4 v[224:227], v13, s[8:11], s40 offen nt
	buffer_load_dwordx4 v[228:231], v13, s[8:11], s41 offen nt
	buffer_load_dwordx4 v[232:235], v13, s[8:11], s42 offen nt
	buffer_load_dwordx4 v[236:239], v13, s[8:11], s43 offen nt
	v_max3_f32 v10, v10, |v6|, |v24|
	v_max3_f32 v11, v11, |v7|, |v25|
	v_max3_f32 v12, v12, |v8|, |v26|
	v_max3_f32 v14, v14, |v9|, |v27|
	v_max3_f32 v10, v10, |v28|, |v32|
	v_max3_f32 v11, v11, |v29|, |v33|
	v_max3_f32 v12, v12, |v30|, |v34|
	v_max3_f32 v14, v14, |v31|, |v35|
	v_max3_f32 v10, v10, |v36|, |v42|
	v_max3_f32 v11, v11, |v37|, |v43|
	v_max3_f32 v12, v12, |v38|, |v44|
	v_max3_f32 v14, v14, |v39|, |v45|
	v_max3_f32 v10, v10, |v46|, |v50|
	v_max3_f32 v11, v11, |v47|, |v51|
	v_max3_f32 v54, v12, |v48|, |v52|
	v_max3_f32 v55, v14, |v49|, |v53|
	v_cvt_pk_bf16_f32 v72, v6, v24
	v_cvt_pk_bf16_f32 v15, v28, v32
	v_cvt_pk_bf16_f32 v14, v36, v42
	v_cvt_pk_bf16_f32 v12, v46, v50
	v_cvt_pk_bf16_f32 v59, v7, v25
	v_cvt_pk_bf16_f32 v58, v29, v33
	v_cvt_pk_bf16_f32 v57, v37, v43
	v_cvt_pk_bf16_f32 v56, v47, v51
	v_cvt_pk_bf16_f32 v43, v8, v26
	v_cvt_pk_bf16_f32 v42, v30, v34
	v_cvt_pk_bf16_f32 v41, v38, v44
	v_cvt_pk_bf16_f32 v40, v48, v52
	v_cvt_pk_bf16_f32 v27, v9, v27
	v_cvt_pk_bf16_f32 v26, v31, v35
	v_cvt_pk_bf16_f32 v25, v39, v45
	v_cvt_pk_bf16_f32 v24, v49, v53
	s_waitcnt vmcnt(8)
	v_mov_b32_e32 v6, v164
	v_mov_b32_e32 v7, v165
	v_mov_b32_e32 v8, v166
	v_mov_b32_e32 v9, v167
	v_mov_b32_e32 v28, v168
	v_mov_b32_e32 v29, v169
	v_mov_b32_e32 v30, v170
	v_mov_b32_e32 v31, v171
	v_mov_b32_e32 v32, v172
	v_mov_b32_e32 v33, v173
	v_mov_b32_e32 v34, v174
	v_mov_b32_e32 v35, v175
	v_mov_b32_e32 v36, v176
	v_mov_b32_e32 v37, v177
	v_mov_b32_e32 v38, v178
	v_mov_b32_e32 v39, v179
	v_mov_b32_e32 v46, v180
	v_mov_b32_e32 v47, v181
	v_mov_b32_e32 v48, v182
	v_mov_b32_e32 v49, v183
	v_mov_b32_e32 v50, v184
	v_mov_b32_e32 v51, v185
	v_mov_b32_e32 v52, v186
	v_mov_b32_e32 v53, v187
	v_mov_b32_e32 v64, v188
	v_mov_b32_e32 v65, v189
	v_mov_b32_e32 v66, v190
	v_mov_b32_e32 v67, v191
	v_mov_b32_e32 v68, v192
	v_mov_b32_e32 v69, v193
	v_mov_b32_e32 v70, v194
	v_mov_b32_e32 v71, v195
	buffer_load_dwordx4 v[164:167], v13, s[8:11], s44 offen nt
	buffer_load_dwordx4 v[168:171], v13, s[8:11], s45 offen nt
	buffer_load_dwordx4 v[172:175], v13, s[8:11], s46 offen nt
	buffer_load_dwordx4 v[176:179], v13, s[8:11], s47 offen nt
	buffer_load_dwordx4 v[180:183], v13, s[8:11], s48 offen nt
	buffer_load_dwordx4 v[184:187], v13, s[8:11], s49 offen nt
	buffer_load_dwordx4 v[188:191], v13, s[8:11], s50 offen nt
	buffer_load_dwordx4 v[192:195], v13, s[8:11], s51 offen nt
	v_max3_f32 v10, v10, |v6|, |v28|
	v_max3_f32 v11, v11, |v7|, |v29|
	v_max3_f32 v44, v54, |v8|, |v30|
	v_max3_f32 v45, v55, |v9|, |v31|
	v_max3_f32 v10, v10, |v32|, |v36|
	v_max3_f32 v11, v11, |v33|, |v37|
	v_max3_f32 v44, v44, |v34|, |v38|
	v_max3_f32 v45, v45, |v35|, |v39|
	v_max3_f32 v10, v10, |v46|, |v50|
	v_max3_f32 v11, v11, |v47|, |v51|
	v_max3_f32 v44, v44, |v48|, |v52|
	v_max3_f32 v45, v45, |v49|, |v53|
	v_max3_f32 v10, v10, |v64|, |v68|
	v_max3_f32 v11, v11, |v65|, |v69|
	v_max3_f32 v54, v44, |v66|, |v70|
	v_max3_f32 v55, v45, |v67|, |v71|
	v_cvt_pk_bf16_f32 v76, v6, v28
	v_cvt_pk_bf16_f32 v75, v32, v36
	v_cvt_pk_bf16_f32 v74, v46, v50
	v_cvt_pk_bf16_f32 v73, v64, v68
	v_cvt_pk_bf16_f32 v63, v7, v29
	v_cvt_pk_bf16_f32 v62, v33, v37
	v_cvt_pk_bf16_f32 v61, v47, v51
	v_cvt_pk_bf16_f32 v60, v65, v69
	v_cvt_pk_bf16_f32 v47, v8, v30
	v_cvt_pk_bf16_f32 v46, v34, v38
	v_cvt_pk_bf16_f32 v45, v48, v52
	v_cvt_pk_bf16_f32 v44, v66, v70
	v_cvt_pk_bf16_f32 v31, v9, v31
	v_cvt_pk_bf16_f32 v30, v35, v39
	v_cvt_pk_bf16_f32 v29, v49, v53
	v_cvt_pk_bf16_f32 v28, v67, v71
	s_waitcnt vmcnt(8)
	v_mov_b32_e32 v6, v208
	v_mov_b32_e32 v7, v209
	v_mov_b32_e32 v8, v210
	v_mov_b32_e32 v9, v211
	v_mov_b32_e32 v32, v212
	v_mov_b32_e32 v33, v213
	v_mov_b32_e32 v34, v214
	v_mov_b32_e32 v35, v215
	v_mov_b32_e32 v36, v216
	v_mov_b32_e32 v37, v217
	v_mov_b32_e32 v38, v218
	v_mov_b32_e32 v39, v219
	v_mov_b32_e32 v50, v220
	v_mov_b32_e32 v51, v221
	v_mov_b32_e32 v52, v222
	v_mov_b32_e32 v53, v223
	v_mov_b32_e32 v68, v224
	v_mov_b32_e32 v69, v225
	v_mov_b32_e32 v70, v226
	v_mov_b32_e32 v71, v227
	v_mov_b32_e32 v82, v228
	v_mov_b32_e32 v83, v229
	v_mov_b32_e32 v84, v230
	v_mov_b32_e32 v85, v231
	v_mov_b32_e32 v86, v232
	v_mov_b32_e32 v87, v233
	v_mov_b32_e32 v88, v234
	v_mov_b32_e32 v89, v235
	v_mov_b32_e32 v90, v236
	v_mov_b32_e32 v91, v237
	v_mov_b32_e32 v92, v238
	v_mov_b32_e32 v93, v239
	v_max3_f32 v10, v10, |v6|, |v32|
	v_max3_f32 v11, v11, |v7|, |v33|
	v_max3_f32 v48, v54, |v8|, |v34|
	v_max3_f32 v49, v55, |v9|, |v35|
	v_max3_f32 v10, v10, |v36|, |v50|
	v_max3_f32 v11, v11, |v37|, |v51|
	v_max3_f32 v48, v48, |v38|, |v52|
	v_max3_f32 v49, v49, |v39|, |v53|
	v_max3_f32 v10, v10, |v68|, |v82|
	v_max3_f32 v11, v11, |v69|, |v83|
	v_max3_f32 v48, v48, |v70|, |v84|
	v_max3_f32 v49, v49, |v71|, |v85|
	v_max3_f32 v10, v10, |v86|, |v90|
	v_max3_f32 v11, v11, |v87|, |v91|
	v_max3_f32 v54, v48, |v88|, |v92|
	v_max3_f32 v55, v49, |v89|, |v93|
	v_cvt_pk_bf16_f32 v80, v6, v32
	v_cvt_pk_bf16_f32 v79, v36, v50
	v_cvt_pk_bf16_f32 v78, v68, v82
	v_cvt_pk_bf16_f32 v77, v86, v90
	v_cvt_pk_bf16_f32 v67, v7, v33
	v_cvt_pk_bf16_f32 v66, v37, v51
	v_cvt_pk_bf16_f32 v65, v69, v83
	v_cvt_pk_bf16_f32 v64, v87, v91
	v_cvt_pk_bf16_f32 v51, v8, v34
	v_cvt_pk_bf16_f32 v50, v38, v52
	v_cvt_pk_bf16_f32 v49, v70, v84
	v_cvt_pk_bf16_f32 v48, v88, v92
	v_cvt_pk_bf16_f32 v35, v9, v35
	v_cvt_pk_bf16_f32 v34, v39, v53
	v_cvt_pk_bf16_f32 v33, v71, v85
	v_cvt_pk_bf16_f32 v32, v89, v93
	s_waitcnt vmcnt(0)
	v_mov_b32_e32 v6, v164
	v_mov_b32_e32 v7, v165
	v_mov_b32_e32 v8, v166
	v_mov_b32_e32 v9, v167
	v_mov_b32_e32 v36, v168
	v_mov_b32_e32 v37, v169
	v_mov_b32_e32 v38, v170
	v_mov_b32_e32 v39, v171
	v_mov_b32_e32 v86, v172
	v_mov_b32_e32 v87, v173
	v_mov_b32_e32 v88, v174
	v_mov_b32_e32 v89, v175
	v_mov_b32_e32 v90, v176
	v_mov_b32_e32 v91, v177
	v_mov_b32_e32 v92, v178
	v_mov_b32_e32 v93, v179
	v_mov_b32_e32 v94, v180
	v_mov_b32_e32 v95, v181
	v_mov_b32_e32 v96, v182
	v_mov_b32_e32 v97, v183
	v_mov_b32_e32 v98, v184
	v_mov_b32_e32 v99, v185
	v_mov_b32_e32 v100, v186
	v_mov_b32_e32 v101, v187
	v_mov_b32_e32 v102, v188
	v_mov_b32_e32 v103, v189
	v_mov_b32_e32 v104, v190
	v_mov_b32_e32 v105, v191
	v_mov_b32_e32 v106, v192
	v_mov_b32_e32 v107, v193
	v_mov_b32_e32 v108, v194
	v_mov_b32_e32 v109, v195
	v_max3_f32 v10, v10, |v6|, |v36|
	v_max3_f32 v11, v11, |v7|, |v37|
	v_max3_f32 v52, v54, |v8|, |v38|
	v_max3_f32 v53, v55, |v9|, |v39|
	v_max3_f32 v10, v10, |v86|, |v90|
	v_max3_f32 v11, v11, |v87|, |v91|
	v_max3_f32 v52, v52, |v88|, |v92|
	v_max3_f32 v53, v53, |v89|, |v93|
	v_max3_f32 v10, v10, |v94|, |v98|
	v_max3_f32 v11, v11, |v95|, |v99|
	v_max3_f32 v52, v52, |v96|, |v100|
	v_max3_f32 v53, v53, |v97|, |v101|
	v_max3_f32 v10, v10, |v102|, |v106|
	v_max3_f32 v11, v11, |v103|, |v107|
	v_max3_f32 v85, v52, |v104|, |v108|
	v_max3_f32 v110, v53, |v105|, |v109|
	v_cvt_pk_bf16_f32 v84, v6, v36
	v_cvt_pk_bf16_f32 v83, v86, v90
	v_cvt_pk_bf16_f32 v82, v94, v98
	v_cvt_pk_bf16_f32 v81, v102, v106
	v_cvt_pk_bf16_f32 v71, v7, v37
	v_cvt_pk_bf16_f32 v70, v87, v91
	v_cvt_pk_bf16_f32 v69, v95, v99
	v_cvt_pk_bf16_f32 v68, v103, v107
	v_cvt_pk_bf16_f32 v55, v8, v38
	v_cvt_pk_bf16_f32 v54, v88, v92
	v_cvt_pk_bf16_f32 v53, v96, v100
	v_cvt_pk_bf16_f32 v52, v104, v108
	v_cvt_pk_bf16_f32 v39, v9, v39
	v_cvt_pk_bf16_f32 v38, v89, v93
	v_cvt_pk_bf16_f32 v37, v97, v101
	v_cvt_pk_bf16_f32 v36, v105, v109
	v_cmp_lt_i32_e32 vcc, v21, v20
	s_nop 1
	v_cndmask_b32_e32 v6, v19, v21, vcc
	v_lshlrev_b32_e32 v6, 2, v6
	ds_bpermute_b32 v7, v6, v10
	ds_bpermute_b32 v8, v6, v11
	v_cmp_lt_i32_e32 vcc, v22, v20
	ds_bpermute_b32 v9, v6, v85
	ds_bpermute_b32 v6, v6, v110
	s_waitcnt lgkmcnt(3)
	v_max_f32_e32 v7, v7, v7
	v_max_f32_e32 v7, v10, v7
	v_cndmask_b32_e32 v10, v19, v22, vcc
	s_waitcnt lgkmcnt(2)
	v_max_f32_e32 v8, v8, v8
	v_lshlrev_b32_e32 v10, 2, v10
	v_max_f32_e32 v8, v11, v8
	ds_bpermute_b32 v11, v10, v7
	s_waitcnt lgkmcnt(2)
	v_max_f32_e32 v9, v9, v9
	s_waitcnt lgkmcnt(1)
	v_max_f32_e32 v6, v6, v6
	v_max_f32_e32 v85, v85, v9
	v_max_f32_e32 v86, v110, v6
	ds_bpermute_b32 v9, v10, v8
	s_waitcnt lgkmcnt(1)
	v_max_f32_e32 v6, v11, v11
	ds_bpermute_b32 v11, v10, v85
	v_max_f32_e32 v6, v7, v6
	ds_bpermute_b32 v7, v10, v86
	s_waitcnt lgkmcnt(2)
	v_max_f32_e32 v9, v9, v9
	v_cmp_lt_i32_e32 vcc, v23, v20
	v_max_f32_e32 v9, v8, v9
	s_waitcnt lgkmcnt(1)
	v_max_f32_e32 v8, v11, v11
	s_waitcnt lgkmcnt(0)
	v_max_f32_e32 v7, v7, v7
	v_cndmask_b32_e32 v10, v19, v23, vcc
	v_max_f32_e32 v8, v85, v8
	v_max_f32_e32 v7, v86, v7
	v_lshlrev_b32_e32 v10, 2, v10
	ds_bpermute_b32 v86, v10, v6
	ds_bpermute_b32 v85, v10, v9
	ds_bpermute_b32 v11, v10, v8
	ds_bpermute_b32 v10, v10, v7
	s_and_saveexec_b64 s[2:3], s[4:5]
	s_cbranch_execz .LBB0_105
	s_waitcnt lgkmcnt(3)
	v_max_f32_e32 v86, v86, v86
	v_max_f32_e32 v6, v6, v6
	v_max_f32_e32 v86, v6, v86
	s_waitcnt lgkmcnt(2)
	v_max_f32_e32 v6, v85, v85
	v_max_f32_e32 v9, v9, v9
	v_max_f32_e32 v87, v9, v6
	s_waitcnt lgkmcnt(1)
	v_max_f32_e32 v6, v11, v11
	v_max_f32_e32 v8, v8, v8
	v_max_f32_e32 v88, v8, v6
	s_waitcnt lgkmcnt(0)
	v_max_f32_e32 v6, v10, v10
	v_max_f32_e32 v7, v7, v7
	v_max_f32_e32 v89, v7, v6
	ds_write_b128 v17, v[86:89]

.LBB0_196:
	s_bitcmp0_b32 s33, 2
	s_waitcnt lgkmcnt(0)
	s_cselect_b32 s1, s75, s77
	s_cselect_b32 s3, s74, s76
	s_and_b32 s2, s18, 0xffffff80
	s_and_b32 s8, s0, 0x60
	s_or_b32 s2, s2, s8
	v_readlane_b32 s8, v248, 0
	s_mul_i32 s8, s8, 0x1580000
	s_add_u32 s8, s3, s8
	s_addc_u32 s1, s1, s16
	s_ashr_i32 s3, s2, 31
	s_lshl_b64 s[2:3], s[2:3], 2
	s_add_u32 s8, s8, s2
	s_addc_u32 s1, s1, s3
	s_and_b32 s9, s1, 0xffff
	s_mov_b32 s1, 0xac00
	buffer_load_dwordx4 v[208:211], v16, s[8:11], 0 offen nt
	buffer_load_dwordx4 v[212:215], v16, s[8:11], s1 offen nt
	s_mov_b32 s1, 0x15800
	buffer_load_dwordx4 v[216:219], v16, s[8:11], s1 offen nt
	s_mov_b32 s1, 0x20400
	buffer_load_dwordx4 v[220:223], v16, s[8:11], s1 offen nt
	s_mov_b32 s1, 0x2b000
	buffer_load_dwordx4 v[224:227], v16, s[8:11], s1 offen nt
	s_mov_b32 s1, 0x35c00
	buffer_load_dwordx4 v[228:231], v16, s[8:11], s1 offen nt
	s_mov_b32 s1, 0x40800
	buffer_load_dwordx4 v[232:235], v16, s[8:11], s1 offen nt
	s_mov_b32 s1, 0x4b400
	buffer_load_dwordx4 v[236:239], v16, s[8:11], s1 offen nt
	s_mov_b32 s1, 0x56000
	buffer_load_dwordx4 v[164:167], v16, s[8:11], s1 offen nt
	s_mov_b32 s1, 0x60c00
	buffer_load_dwordx4 v[168:171], v16, s[8:11], s1 offen nt
	s_mov_b32 s1, 0x6b800
	buffer_load_dwordx4 v[172:175], v16, s[8:11], s1 offen nt
	s_mov_b32 s1, 0x76400
	buffer_load_dwordx4 v[176:179], v16, s[8:11], s1 offen nt
	s_mov_b32 s1, 0x81000
	buffer_load_dwordx4 v[180:183], v16, s[8:11], s1 offen nt
	s_mov_b32 s1, 0x8bc00
	buffer_load_dwordx4 v[184:187], v16, s[8:11], s1 offen nt
	s_mov_b32 s1, 0x96800
	buffer_load_dwordx4 v[188:191], v16, s[8:11], s1 offen nt
	s_mov_b32 s1, 0xa1400
	buffer_load_dwordx4 v[192:195], v16, s[8:11], s1 offen nt
	s_waitcnt vmcnt(8)
	v_mov_b32_e32 v6, v208
	v_mov_b32_e32 v7, v209
	v_mov_b32_e32 v8, v210
	v_mov_b32_e32 v9, v211
	v_mov_b32_e32 v26, v212
	v_mov_b32_e32 v27, v213
	v_mov_b32_e32 v28, v214
	v_mov_b32_e32 v29, v215
	v_mov_b32_e32 v30, v216
	v_mov_b32_e32 v31, v217
	v_mov_b32_e32 v32, v218
	v_mov_b32_e32 v33, v219
	v_mov_b32_e32 v34, v220
	v_mov_b32_e32 v35, v221
	v_mov_b32_e32 v36, v222
	v_mov_b32_e32 v37, v223
	v_mov_b32_e32 v38, v224
	v_mov_b32_e32 v39, v225
	v_mov_b32_e32 v40, v226
	v_mov_b32_e32 v41, v227
	v_mov_b32_e32 v42, v228
	v_mov_b32_e32 v43, v229
	v_mov_b32_e32 v44, v230
	v_mov_b32_e32 v45, v231
	v_mov_b32_e32 v46, v232
	v_mov_b32_e32 v47, v233
	v_mov_b32_e32 v48, v234
	v_mov_b32_e32 v49, v235
	v_mov_b32_e32 v50, v236
	v_mov_b32_e32 v51, v237
	v_mov_b32_e32 v52, v238
	v_mov_b32_e32 v53, v239
	s_mov_b32 s1, 0xac000
	buffer_load_dwordx4 v[208:211], v16, s[8:11], s1 offen nt
	s_mov_b32 s1, 0xb6c00
	buffer_load_dwordx4 v[212:215], v16, s[8:11], s1 offen nt
	s_mov_b32 s1, 0xc1800
	buffer_load_dwordx4 v[216:219], v16, s[8:11], s1 offen nt
	s_mov_b32 s1, 0xcc400
	buffer_load_dwordx4 v[220:223], v16, s[8:11], s1 offen nt
	s_mov_b32 s1, 0xd7000
	buffer_load_dwordx4 v[224:227], v16, s[8:11], s1 offen nt
	s_mov_b32 s1, 0xe1c00
	buffer_load_dwordx4 v[228:231], v16, s[8:11], s1 offen nt
	s_mov_b32 s1, 0xec800
	buffer_load_dwordx4 v[232:235], v16, s[8:11], s1 offen nt
	s_mov_b32 s1, 0xf7400
	buffer_load_dwordx4 v[236:239], v16, s[8:11], s1 offen nt
	v_max3_f32 v10, |v6|, 0, |v26|
	v_max3_f32 v11, |v7|, 0, |v27|
	v_max3_f32 v12, |v8|, 0, |v28|
	v_max3_f32 v14, |v9|, 0, |v29|
	v_max3_f32 v10, v10, |v30|, |v34|
	v_max3_f32 v11, v11, |v31|, |v35|
	v_max3_f32 v12, v12, |v32|, |v36|
	v_max3_f32 v14, v14, |v33|, |v37|
	v_max3_f32 v10, v10, |v38|, |v42|
	v_max3_f32 v11, v11, |v39|, |v43|
	v_max3_f32 v12, v12, |v40|, |v44|
	v_max3_f32 v14, v14, |v41|, |v45|
	v_cvt_pk_bf16_f32 v54, v6, v26
	v_cvt_pk_bf16_f32 v55, v30, v34
	v_cvt_pk_bf16_f32 v56, v38, v42
	v_cvt_pk_bf16_f32 v57, v46, v50
	v_max3_f32 v10, v10, |v46|, |v50|
	v_max3_f32 v11, v11, |v47|, |v51|
	v_max3_f32 v12, v12, |v48|, |v52|
	v_max3_f32 v14, v14, |v49|, |v53|
	ds_write_b128 v19, v[54:57]
	v_cvt_pk_bf16_f32 v54, v7, v27
	v_cvt_pk_bf16_f32 v55, v31, v35
	v_cvt_pk_bf16_f32 v56, v39, v43
	v_cvt_pk_bf16_f32 v57, v47, v51
	ds_write_b128 v19, v[54:57] offset:1024
	v_cvt_pk_bf16_f32 v54, v8, v28
	v_cvt_pk_bf16_f32 v55, v32, v36
	v_cvt_pk_bf16_f32 v56, v40, v44
	v_cvt_pk_bf16_f32 v57, v48, v52
	ds_write_b128 v19, v[54:57] offset:2048
	v_cvt_pk_bf16_f32 v6, v9, v29
	v_cvt_pk_bf16_f32 v7, v33, v37
	v_cvt_pk_bf16_f32 v8, v41, v45
	v_cvt_pk_bf16_f32 v9, v49, v53
	ds_write_b128 v19, v[6:9] offset:3072
	s_waitcnt vmcnt(8)
	v_mov_b32_e32 v6, v164
	v_mov_b32_e32 v7, v165
	v_mov_b32_e32 v8, v166
	v_mov_b32_e32 v9, v167
	v_mov_b32_e32 v26, v168
	v_mov_b32_e32 v27, v169
	v_mov_b32_e32 v28, v170
	v_mov_b32_e32 v29, v171
	v_mov_b32_e32 v30, v172
	v_mov_b32_e32 v31, v173
	v_mov_b32_e32 v32, v174
	v_mov_b32_e32 v33, v175
	v_mov_b32_e32 v34, v176
	v_mov_b32_e32 v35, v177
	v_mov_b32_e32 v36, v178
	v_mov_b32_e32 v37, v179
	v_mov_b32_e32 v38, v180
	v_mov_b32_e32 v39, v181
	v_mov_b32_e32 v40, v182
	v_mov_b32_e32 v41, v183
	v_mov_b32_e32 v42, v184
	v_mov_b32_e32 v43, v185
	v_mov_b32_e32 v44, v186
	v_mov_b32_e32 v45, v187
	v_mov_b32_e32 v46, v188
	v_mov_b32_e32 v47, v189
	v_mov_b32_e32 v48, v190
	v_mov_b32_e32 v49, v191
	v_mov_b32_e32 v50, v192
	v_mov_b32_e32 v51, v193
	v_mov_b32_e32 v52, v194
	v_mov_b32_e32 v53, v195
	s_mov_b32 s1, 0x102000
	buffer_load_dwordx4 v[164:167], v16, s[8:11], s1 offen nt
	s_mov_b32 s1, 0x10cc00
	buffer_load_dwordx4 v[168:171], v16, s[8:11], s1 offen nt
	s_mov_b32 s1, 0x117800
	buffer_load_dwordx4 v[172:175], v16, s[8:11], s1 offen nt
	s_mov_b32 s1, 0x122400
	buffer_load_dwordx4 v[176:179], v16, s[8:11], s1 offen nt
	s_mov_b32 s1, 0x12d000
	buffer_load_dwordx4 v[180:183], v16, s[8:11], s1 offen nt
	s_mov_b32 s1, 0x137c00
	buffer_load_dwordx4 v[184:187], v16, s[8:11], s1 offen nt
	s_mov_b32 s1, 0x142800
	buffer_load_dwordx4 v[188:191], v16, s[8:11], s1 offen nt
	s_mov_b32 s1, 0x14d400
	buffer_load_dwordx4 v[192:195], v16, s[8:11], s1 offen nt
	v_max3_f32 v10, v10, |v6|, |v26|
	v_max3_f32 v11, v11, |v7|, |v27|
	v_max3_f32 v12, v12, |v8|, |v28|
	v_max3_f32 v14, v14, |v9|, |v29|
	v_max3_f32 v10, v10, |v30|, |v34|
	v_max3_f32 v11, v11, |v31|, |v35|
	v_max3_f32 v12, v12, |v32|, |v36|
	v_max3_f32 v14, v14, |v33|, |v37|
	v_max3_f32 v10, v10, |v38|, |v42|
	v_max3_f32 v11, v11, |v39|, |v43|
	v_max3_f32 v12, v12, |v40|, |v44|
	v_max3_f32 v14, v14, |v41|, |v45|
	v_cvt_pk_bf16_f32 v54, v6, v26
	v_cvt_pk_bf16_f32 v55, v30, v34
	v_cvt_pk_bf16_f32 v56, v38, v42
	v_cvt_pk_bf16_f32 v57, v46, v50
	v_max3_f32 v10, v10, |v46|, |v50|
	v_max3_f32 v11, v11, |v47|, |v51|
	v_max3_f32 v12, v12, |v48|, |v52|
	v_max3_f32 v14, v14, |v49|, |v53|
	ds_write_b128 v19, v[54:57] offset:4096
	v_cvt_pk_bf16_f32 v54, v7, v27
	v_cvt_pk_bf16_f32 v55, v31, v35
	v_cvt_pk_bf16_f32 v56, v39, v43
	v_cvt_pk_bf16_f32 v57, v47, v51
	ds_write_b128 v19, v[54:57] offset:5120
	v_cvt_pk_bf16_f32 v54, v8, v28
	v_cvt_pk_bf16_f32 v55, v32, v36
	v_cvt_pk_bf16_f32 v56, v40, v44
	v_cvt_pk_bf16_f32 v57, v48, v52
	ds_write_b128 v19, v[54:57] offset:6144
	v_cvt_pk_bf16_f32 v6, v9, v29
	v_cvt_pk_bf16_f32 v7, v33, v37
	v_cvt_pk_bf16_f32 v8, v41, v45
	v_cvt_pk_bf16_f32 v9, v49, v53
	ds_write_b128 v19, v[6:9] offset:7168
	s_waitcnt vmcnt(8)
	v_mov_b32_e32 v6, v208
	v_mov_b32_e32 v7, v209
	v_mov_b32_e32 v8, v210
	v_mov_b32_e32 v9, v211
	v_mov_b32_e32 v26, v212
	v_mov_b32_e32 v27, v213
	v_mov_b32_e32 v28, v214
	v_mov_b32_e32 v29, v215
	v_mov_b32_e32 v30, v216
	v_mov_b32_e32 v31, v217
	v_mov_b32_e32 v32, v218
	v_mov_b32_e32 v33, v219
	v_mov_b32_e32 v34, v220
	v_mov_b32_e32 v35, v221
	v_mov_b32_e32 v36, v222
	v_mov_b32_e32 v37, v223
	v_mov_b32_e32 v38, v224
	v_mov_b32_e32 v39, v225
	v_mov_b32_e32 v40, v226
	v_mov_b32_e32 v41, v227
	v_mov_b32_e32 v42, v228
	v_mov_b32_e32 v43, v229
	v_mov_b32_e32 v44, v230
	v_mov_b32_e32 v45, v231
	v_mov_b32_e32 v46, v232
	v_mov_b32_e32 v47, v233
	v_mov_b32_e32 v48, v234
	v_mov_b32_e32 v49, v235
	v_mov_b32_e32 v50, v236
	v_mov_b32_e32 v51, v237
	v_mov_b32_e32 v52, v238
	v_mov_b32_e32 v53, v239
	s_mov_b32 s1, 0x158000
	buffer_load_dwordx4 v[208:211], v16, s[8:11], s1 offen nt
	s_mov_b32 s1, 0x162c00
	buffer_load_dwordx4 v[212:215], v16, s[8:11], s1 offen nt
	s_mov_b32 s1, 0x16d800
	buffer_load_dwordx4 v[216:219], v16, s[8:11], s1 offen nt
	s_mov_b32 s1, 0x178400
	buffer_load_dwordx4 v[220:223], v16, s[8:11], s1 offen nt
	s_mov_b32 s1, 0x183000
	buffer_load_dwordx4 v[224:227], v16, s[8:11], s1 offen nt
	s_mov_b32 s1, 0x18dc00
	buffer_load_dwordx4 v[228:231], v16, s[8:11], s1 offen nt
	s_mov_b32 s1, 0x198800
	buffer_load_dwordx4 v[232:235], v16, s[8:11], s1 offen nt
	s_mov_b32 s1, 0x1a3400
	buffer_load_dwordx4 v[236:239], v16, s[8:11], s1 offen nt
	v_max3_f32 v10, v10, |v6|, |v26|
	v_max3_f32 v11, v11, |v7|, |v27|
	v_max3_f32 v12, v12, |v8|, |v28|
	v_max3_f32 v14, v14, |v9|, |v29|
	v_max3_f32 v10, v10, |v30|, |v34|
	v_max3_f32 v11, v11, |v31|, |v35|
	v_max3_f32 v12, v12, |v32|, |v36|
	v_max3_f32 v14, v14, |v33|, |v37|
	v_max3_f32 v10, v10, |v38|, |v42|
	v_max3_f32 v11, v11, |v39|, |v43|
	v_max3_f32 v12, v12, |v40|, |v44|
	v_max3_f32 v14, v14, |v41|, |v45|
	v_cvt_pk_bf16_f32 v54, v6, v26
	v_cvt_pk_bf16_f32 v55, v30, v34
	v_cvt_pk_bf16_f32 v56, v38, v42
	v_cvt_pk_bf16_f32 v57, v46, v50
	v_max3_f32 v10, v10, |v46|, |v50|
	v_max3_f32 v11, v11, |v47|, |v51|
	v_max3_f32 v12, v12, |v48|, |v52|
	v_max3_f32 v14, v14, |v49|, |v53|
	ds_write_b128 v19, v[54:57] offset:8192
	v_cvt_pk_bf16_f32 v54, v7, v27
	v_cvt_pk_bf16_f32 v55, v31, v35
	v_cvt_pk_bf16_f32 v56, v39, v43
	v_cvt_pk_bf16_f32 v57, v47, v51
	ds_write_b128 v19, v[54:57] offset:9216
	v_cvt_pk_bf16_f32 v54, v8, v28
	v_cvt_pk_bf16_f32 v55, v32, v36
	v_cvt_pk_bf16_f32 v56, v40, v44
	v_cvt_pk_bf16_f32 v57, v48, v52
	ds_write_b128 v19, v[54:57] offset:10240
	v_cvt_pk_bf16_f32 v6, v9, v29
	v_cvt_pk_bf16_f32 v7, v33, v37
	v_cvt_pk_bf16_f32 v8, v41, v45
	v_cvt_pk_bf16_f32 v9, v49, v53
	ds_write_b128 v19, v[6:9] offset:11264
	s_waitcnt vmcnt(8)
	v_mov_b32_e32 v6, v164
	v_mov_b32_e32 v7, v165
	v_mov_b32_e32 v8, v166
	v_mov_b32_e32 v9, v167
	v_mov_b32_e32 v26, v168
	v_mov_b32_e32 v27, v169
	v_mov_b32_e32 v28, v170
	v_mov_b32_e32 v29, v171
	v_mov_b32_e32 v30, v172
	v_mov_b32_e32 v31, v173
	v_mov_b32_e32 v32, v174
	v_mov_b32_e32 v33, v175
	v_mov_b32_e32 v34, v176
	v_mov_b32_e32 v35, v177
	v_mov_b32_e32 v36, v178
	v_mov_b32_e32 v37, v179
	v_mov_b32_e32 v38, v180
	v_mov_b32_e32 v39, v181
	v_mov_b32_e32 v40, v182
	v_mov_b32_e32 v41, v183
	v_mov_b32_e32 v42, v184
	v_mov_b32_e32 v43, v185
	v_mov_b32_e32 v44, v186
	v_mov_b32_e32 v45, v187
	v_mov_b32_e32 v46, v188
	v_mov_b32_e32 v47, v189
	v_mov_b32_e32 v48, v190
	v_mov_b32_e32 v49, v191
	v_mov_b32_e32 v50, v192
	v_mov_b32_e32 v51, v193
	v_mov_b32_e32 v52, v194
	v_mov_b32_e32 v53, v195
	s_mov_b32 s1, 0x1ae000
	buffer_load_dwordx4 v[164:167], v16, s[8:11], s1 offen nt
	s_mov_b32 s1, 0x1b8c00
	buffer_load_dwordx4 v[168:171], v16, s[8:11], s1 offen nt
	s_mov_b32 s1, 0x1c3800
	buffer_load_dwordx4 v[172:175], v16, s[8:11], s1 offen nt
	s_mov_b32 s1, 0x1ce400
	buffer_load_dwordx4 v[176:179], v16, s[8:11], s1 offen nt
	s_mov_b32 s1, 0x1d9000
	buffer_load_dwordx4 v[180:183], v16, s[8:11], s1 offen nt
	s_mov_b32 s1, 0x1e3c00
	buffer_load_dwordx4 v[184:187], v16, s[8:11], s1 offen nt
	s_mov_b32 s1, 0x1ee800
	buffer_load_dwordx4 v[188:191], v16, s[8:11], s1 offen nt
	s_mov_b32 s1, 0x1f9400
	buffer_load_dwordx4 v[192:195], v16, s[8:11], s1 offen nt
	v_max3_f32 v10, v10, |v6|, |v26|
	v_max3_f32 v11, v11, |v7|, |v27|
	v_max3_f32 v12, v12, |v8|, |v28|
	v_max3_f32 v14, v14, |v9|, |v29|
	v_max3_f32 v10, v10, |v30|, |v34|
	v_max3_f32 v11, v11, |v31|, |v35|
	v_max3_f32 v12, v12, |v32|, |v36|
	v_max3_f32 v14, v14, |v33|, |v37|
	v_max3_f32 v10, v10, |v38|, |v42|
	v_max3_f32 v11, v11, |v39|, |v43|
	v_max3_f32 v12, v12, |v40|, |v44|
	v_max3_f32 v14, v14, |v41|, |v45|
	v_cvt_pk_bf16_f32 v54, v6, v26
	v_cvt_pk_bf16_f32 v55, v30, v34
	v_cvt_pk_bf16_f32 v56, v38, v42
	v_cvt_pk_bf16_f32 v57, v46, v50
	v_max3_f32 v10, v10, |v46|, |v50|
	v_max3_f32 v11, v11, |v47|, |v51|
	v_max3_f32 v12, v12, |v48|, |v52|
	v_max3_f32 v14, v14, |v49|, |v53|
	ds_write_b128 v19, v[54:57] offset:12288
	v_cvt_pk_bf16_f32 v54, v7, v27
	v_cvt_pk_bf16_f32 v55, v31, v35
	v_cvt_pk_bf16_f32 v56, v39, v43
	v_cvt_pk_bf16_f32 v57, v47, v51
	ds_write_b128 v19, v[54:57] offset:13312
	v_cvt_pk_bf16_f32 v54, v8, v28
	v_cvt_pk_bf16_f32 v55, v32, v36
	v_cvt_pk_bf16_f32 v56, v40, v44
	v_cvt_pk_bf16_f32 v57, v48, v52
	ds_write_b128 v19, v[54:57] offset:14336
	v_cvt_pk_bf16_f32 v6, v9, v29
	v_cvt_pk_bf16_f32 v7, v33, v37
	v_cvt_pk_bf16_f32 v8, v41, v45
	v_cvt_pk_bf16_f32 v9, v49, v53
	ds_write_b128 v19, v[6:9] offset:15360
	s_waitcnt vmcnt(8)
	v_mov_b32_e32 v6, v208
	v_mov_b32_e32 v7, v209
	v_mov_b32_e32 v8, v210
	v_mov_b32_e32 v9, v211
	v_mov_b32_e32 v26, v212
	v_mov_b32_e32 v27, v213
	v_mov_b32_e32 v28, v214
	v_mov_b32_e32 v29, v215
	v_mov_b32_e32 v30, v216
	v_mov_b32_e32 v31, v217
	v_mov_b32_e32 v32, v218
	v_mov_b32_e32 v33, v219
	v_mov_b32_e32 v34, v220
	v_mov_b32_e32 v35, v221
	v_mov_b32_e32 v36, v222
	v_mov_b32_e32 v37, v223
	v_mov_b32_e32 v44, v224
	v_mov_b32_e32 v45, v225
	v_mov_b32_e32 v46, v226
	v_mov_b32_e32 v47, v227
	v_mov_b32_e32 v48, v228
	v_mov_b32_e32 v49, v229
	v_mov_b32_e32 v50, v230
	v_mov_b32_e32 v51, v231
	v_mov_b32_e32 v52, v232
	v_mov_b32_e32 v53, v233
	v_mov_b32_e32 v54, v234
	v_mov_b32_e32 v55, v235
	v_mov_b32_e32 v60, v236
	v_mov_b32_e32 v61, v237
	v_mov_b32_e32 v62, v238
	v_mov_b32_e32 v63, v239
	s_mov_b32 s1, 0x204000
	buffer_load_dwordx4 v[208:211], v16, s[8:11], s1 offen nt
	s_mov_b32 s1, 0x20ec00
	buffer_load_dwordx4 v[212:215], v16, s[8:11], s1 offen nt
	s_mov_b32 s1, 0x219800
	buffer_load_dwordx4 v[216:219], v16, s[8:11], s1 offen nt
	s_mov_b32 s1, 0x224400
	buffer_load_dwordx4 v[220:223], v16, s[8:11], s1 offen nt
	s_mov_b32 s1, 0x22f000
	buffer_load_dwordx4 v[224:227], v16, s[8:11], s1 offen nt
	s_mov_b32 s1, 0x239c00
	buffer_load_dwordx4 v[228:231], v16, s[8:11], s1 offen nt
	s_mov_b32 s1, 0x244800
	buffer_load_dwordx4 v[232:235], v16, s[8:11], s1 offen nt
	s_mov_b32 s1, 0x24f400
	buffer_load_dwordx4 v[236:239], v16, s[8:11], s1 offen nt
	v_max3_f32 v10, v10, |v6|, |v26|
	v_max3_f32 v11, v11, |v7|, |v27|
	v_max3_f32 v12, v12, |v8|, |v28|
	v_max3_f32 v14, v14, |v9|, |v29|
	v_max3_f32 v10, v10, |v30|, |v34|
	v_max3_f32 v11, v11, |v31|, |v35|
	v_max3_f32 v12, v12, |v32|, |v36|
	v_max3_f32 v14, v14, |v33|, |v37|
	v_max3_f32 v10, v10, |v44|, |v48|
	v_max3_f32 v11, v11, |v45|, |v49|
	v_max3_f32 v12, v12, |v46|, |v50|
	v_max3_f32 v14, v14, |v47|, |v51|
	v_max3_f32 v10, v10, |v52|, |v60|
	v_max3_f32 v11, v11, |v53|, |v61|
	v_max3_f32 v38, v12, |v54|, |v62|
	v_max3_f32 v39, v14, |v55|, |v63|
	v_cvt_pk_bf16_f32 v73, v6, v26
	v_cvt_pk_bf16_f32 v15, v30, v34
	v_cvt_pk_bf16_f32 v14, v44, v48
	v_cvt_pk_bf16_f32 v12, v52, v60
	v_cvt_pk_bf16_f32 v60, v7, v27
	v_cvt_pk_bf16_f32 v59, v31, v35
	v_cvt_pk_bf16_f32 v58, v45, v49
	v_cvt_pk_bf16_f32 v57, v53, v61
	v_cvt_pk_bf16_f32 v44, v8, v28
	v_cvt_pk_bf16_f32 v43, v32, v36
	v_cvt_pk_bf16_f32 v42, v46, v50
	v_cvt_pk_bf16_f32 v41, v54, v62
	v_cvt_pk_bf16_f32 v28, v9, v29
	v_cvt_pk_bf16_f32 v27, v33, v37
	v_cvt_pk_bf16_f32 v26, v47, v51
	v_cvt_pk_bf16_f32 v25, v55, v63
	s_waitcnt vmcnt(8)
	v_mov_b32_e32 v6, v164
	v_mov_b32_e32 v7, v165
	v_mov_b32_e32 v8, v166
	v_mov_b32_e32 v9, v167
	v_mov_b32_e32 v30, v168
	v_mov_b32_e32 v31, v169
	v_mov_b32_e32 v32, v170
	v_mov_b32_e32 v33, v171
	v_mov_b32_e32 v34, v172
	v_mov_b32_e32 v35, v173
	v_mov_b32_e32 v36, v174
	v_mov_b32_e32 v37, v175
	v_mov_b32_e32 v48, v176
	v_mov_b32_e32 v49, v177
	v_mov_b32_e32 v50, v178
	v_mov_b32_e32 v51, v179
	v_mov_b32_e32 v52, v180
	v_mov_b32_e32 v53, v181
	v_mov_b32_e32 v54, v182
	v_mov_b32_e32 v55, v183
	v_mov_b32_e32 v64, v184
	v_mov_b32_e32 v65, v185
	v_mov_b32_e32 v66, v186
	v_mov_b32_e32 v67, v187
	v_mov_b32_e32 v68, v188
	v_mov_b32_e32 v69, v189
	v_mov_b32_e32 v70, v190
	v_mov_b32_e32 v71, v191
	v_mov_b32_e32 v78, v192
	v_mov_b32_e32 v79, v193
	v_mov_b32_e32 v80, v194
	v_mov_b32_e32 v81, v195
	s_mov_b32 s1, 0x25a000
	buffer_load_dwordx4 v[164:167], v16, s[8:11], s1 offen nt
	s_mov_b32 s1, 0x264c00
	buffer_load_dwordx4 v[168:171], v16, s[8:11], s1 offen nt
	s_mov_b32 s1, 0x26f800
	buffer_load_dwordx4 v[172:175], v16, s[8:11], s1 offen nt
	s_mov_b32 s1, 0x27a400
	buffer_load_dwordx4 v[176:179], v16, s[8:11], s1 offen nt
	s_mov_b32 s1, 0x285000
	buffer_load_dwordx4 v[180:183], v16, s[8:11], s1 offen nt
	s_mov_b32 s1, 0x28fc00
	buffer_load_dwordx4 v[184:187], v16, s[8:11], s1 offen nt
	s_mov_b32 s1, 0x29a800
	buffer_load_dwordx4 v[188:191], v16, s[8:11], s1 offen nt
	s_mov_b32 s1, 0x2a5400
	buffer_load_dwordx4 v[192:195], v16, s[8:11], s1 offen nt
	v_max3_f32 v10, v10, |v6|, |v30|
	v_max3_f32 v11, v11, |v7|, |v31|
	v_max3_f32 v29, v38, |v8|, |v32|
	v_max3_f32 v38, v39, |v9|, |v33|
	v_max3_f32 v10, v10, |v34|, |v48|
	v_max3_f32 v11, v11, |v35|, |v49|
	v_max3_f32 v29, v29, |v36|, |v50|
	v_max3_f32 v38, v38, |v37|, |v51|
	v_max3_f32 v10, v10, |v52|, |v64|
	v_max3_f32 v11, v11, |v53|, |v65|
	v_max3_f32 v29, v29, |v54|, |v66|
	v_max3_f32 v38, v38, |v55|, |v67|
	v_max3_f32 v10, v10, |v68|, |v78|
	v_max3_f32 v11, v11, |v69|, |v79|
	v_max3_f32 v39, v29, |v70|, |v80|
	v_max3_f32 v38, v38, |v71|, |v81|
	v_cvt_pk_bf16_f32 v77, v6, v30
	v_cvt_pk_bf16_f32 v76, v34, v48
	v_cvt_pk_bf16_f32 v75, v52, v64
	v_cvt_pk_bf16_f32 v74, v68, v78
	v_cvt_pk_bf16_f32 v64, v7, v31
	v_cvt_pk_bf16_f32 v63, v35, v49
	v_cvt_pk_bf16_f32 v62, v53, v65
	v_cvt_pk_bf16_f32 v61, v69, v79
	v_cvt_pk_bf16_f32 v48, v8, v32
	v_cvt_pk_bf16_f32 v47, v36, v50
	v_cvt_pk_bf16_f32 v46, v54, v66
	v_cvt_pk_bf16_f32 v45, v70, v80
	v_cvt_pk_bf16_f32 v32, v9, v33
	v_cvt_pk_bf16_f32 v31, v37, v51
	v_cvt_pk_bf16_f32 v30, v55, v67
	v_cvt_pk_bf16_f32 v29, v71, v81
	s_waitcnt vmcnt(8)
	v_mov_b32_e32 v6, v208
	v_mov_b32_e32 v7, v209
	v_mov_b32_e32 v8, v210
	v_mov_b32_e32 v9, v211
	v_mov_b32_e32 v34, v212
	v_mov_b32_e32 v35, v213
	v_mov_b32_e32 v36, v214
	v_mov_b32_e32 v37, v215
	v_mov_b32_e32 v52, v216
	v_mov_b32_e32 v53, v217
	v_mov_b32_e32 v54, v218
	v_mov_b32_e32 v55, v219
	v_mov_b32_e32 v68, v220
	v_mov_b32_e32 v69, v221
	v_mov_b32_e32 v70, v222
	v_mov_b32_e32 v71, v223
	v_mov_b32_e32 v82, v224
	v_mov_b32_e32 v83, v225
	v_mov_b32_e32 v84, v226
	v_mov_b32_e32 v85, v227
	v_mov_b32_e32 v86, v228
	v_mov_b32_e32 v87, v229
	v_mov_b32_e32 v88, v230
	v_mov_b32_e32 v89, v231
	v_mov_b32_e32 v90, v232
	v_mov_b32_e32 v91, v233
	v_mov_b32_e32 v92, v234
	v_mov_b32_e32 v93, v235
	v_mov_b32_e32 v94, v236
	v_mov_b32_e32 v95, v237
	v_mov_b32_e32 v96, v238
	v_mov_b32_e32 v97, v239
	v_max3_f32 v10, v10, |v6|, |v34|
	v_max3_f32 v11, v11, |v7|, |v35|
	v_max3_f32 v33, v39, |v8|, |v36|
	v_max3_f32 v38, v38, |v9|, |v37|
	v_max3_f32 v10, v10, |v52|, |v68|
	v_max3_f32 v11, v11, |v53|, |v69|
	v_max3_f32 v33, v33, |v54|, |v70|
	v_max3_f32 v38, v38, |v55|, |v71|
	v_max3_f32 v10, v10, |v82|, |v86|
	v_max3_f32 v11, v11, |v83|, |v87|
	v_max3_f32 v33, v33, |v84|, |v88|
	v_max3_f32 v38, v38, |v85|, |v89|
	v_max3_f32 v10, v10, |v90|, |v94|
	v_max3_f32 v11, v11, |v91|, |v95|
	v_max3_f32 v39, v33, |v92|, |v96|
	v_max3_f32 v38, v38, |v93|, |v97|
	v_cvt_pk_bf16_f32 v81, v6, v34
	v_cvt_pk_bf16_f32 v80, v52, v68
	v_cvt_pk_bf16_f32 v79, v82, v86
	v_cvt_pk_bf16_f32 v78, v90, v94
	v_cvt_pk_bf16_f32 v68, v7, v35
	v_cvt_pk_bf16_f32 v67, v53, v69
	v_cvt_pk_bf16_f32 v66, v83, v87
	v_cvt_pk_bf16_f32 v65, v91, v95
	v_cvt_pk_bf16_f32 v52, v8, v36
	v_cvt_pk_bf16_f32 v51, v54, v70
	v_cvt_pk_bf16_f32 v50, v84, v88
	v_cvt_pk_bf16_f32 v49, v92, v96
	v_cvt_pk_bf16_f32 v36, v9, v37
	v_cvt_pk_bf16_f32 v35, v55, v71
	v_cvt_pk_bf16_f32 v34, v85, v89
	v_cvt_pk_bf16_f32 v33, v93, v97
	s_waitcnt vmcnt(0)
	v_mov_b32_e32 v6, v164
	v_mov_b32_e32 v7, v165
	v_mov_b32_e32 v8, v166
	v_mov_b32_e32 v9, v167
	v_mov_b32_e32 v86, v168
	v_mov_b32_e32 v87, v169
	v_mov_b32_e32 v88, v170
	v_mov_b32_e32 v89, v171
	v_mov_b32_e32 v90, v172
	v_mov_b32_e32 v91, v173
	v_mov_b32_e32 v92, v174
	v_mov_b32_e32 v93, v175
	v_mov_b32_e32 v94, v176
	v_mov_b32_e32 v95, v177
	v_mov_b32_e32 v96, v178
	v_mov_b32_e32 v97, v179
	v_mov_b32_e32 v98, v180
	v_mov_b32_e32 v99, v181
	v_mov_b32_e32 v100, v182
	v_mov_b32_e32 v101, v183
	v_mov_b32_e32 v102, v184
	v_mov_b32_e32 v103, v185
	v_mov_b32_e32 v104, v186
	v_mov_b32_e32 v105, v187
	v_mov_b32_e32 v106, v188
	v_mov_b32_e32 v107, v189
	v_mov_b32_e32 v108, v190
	v_mov_b32_e32 v109, v191
	v_mov_b32_e32 v110, v192
	v_mov_b32_e32 v111, v193
	v_mov_b32_e32 v112, v194
	v_mov_b32_e32 v113, v195
	v_max3_f32 v10, v10, |v6|, |v86|
	v_max3_f32 v11, v11, |v7|, |v87|
	v_max3_f32 v37, v39, |v8|, |v88|
	v_max3_f32 v38, v38, |v9|, |v89|
	v_max3_f32 v10, v10, |v90|, |v94|
	v_max3_f32 v11, v11, |v91|, |v95|
	v_max3_f32 v37, v37, |v92|, |v96|
	v_max3_f32 v38, v38, |v93|, |v97|
	v_max3_f32 v10, v10, |v98|, |v102|
	v_max3_f32 v11, v11, |v99|, |v103|
	v_max3_f32 v37, v37, |v100|, |v104|
	v_max3_f32 v38, v38, |v101|, |v105|
	v_max3_f32 v10, v10, |v106|, |v110|
	v_max3_f32 v11, v11, |v107|, |v111|
	v_max3_f32 v114, v37, |v108|, |v112|
	v_max3_f32 v115, v38, |v109|, |v113|
	v_cvt_pk_bf16_f32 v85, v6, v86
	v_cvt_pk_bf16_f32 v84, v90, v94
	v_cvt_pk_bf16_f32 v83, v98, v102
	v_cvt_pk_bf16_f32 v82, v106, v110
	v_cvt_pk_bf16_f32 v72, v7, v87
	v_cvt_pk_bf16_f32 v71, v91, v95
	v_cvt_pk_bf16_f32 v70, v99, v103
	v_cvt_pk_bf16_f32 v69, v107, v111
	v_cvt_pk_bf16_f32 v56, v8, v88
	v_cvt_pk_bf16_f32 v55, v92, v96
	v_cvt_pk_bf16_f32 v54, v100, v104
	v_cvt_pk_bf16_f32 v53, v108, v112
	v_cvt_pk_bf16_f32 v40, v9, v89
	v_cvt_pk_bf16_f32 v39, v93, v97
	v_cvt_pk_bf16_f32 v38, v101, v105
	v_cvt_pk_bf16_f32 v37, v109, v113
	v_cmp_lt_i32_e32 vcc, v22, v21
	s_nop 1
	v_cndmask_b32_e32 v6, v20, v22, vcc
	v_lshlrev_b32_e32 v6, 2, v6
	ds_bpermute_b32 v7, v6, v10
	ds_bpermute_b32 v8, v6, v11
	v_cmp_lt_i32_e32 vcc, v23, v21
	ds_bpermute_b32 v9, v6, v114
	ds_bpermute_b32 v6, v6, v115
	s_waitcnt lgkmcnt(3)
	v_max_f32_e32 v7, v7, v7
	v_max_f32_e32 v7, v10, v7
	v_cndmask_b32_e32 v10, v20, v23, vcc
	s_waitcnt lgkmcnt(2)
	v_max_f32_e32 v8, v8, v8
	v_lshlrev_b32_e32 v10, 2, v10
	v_max_f32_e32 v8, v11, v8
	ds_bpermute_b32 v11, v10, v7
	s_waitcnt lgkmcnt(2)
	v_max_f32_e32 v9, v9, v9
	s_waitcnt lgkmcnt(1)
	v_max_f32_e32 v6, v6, v6
	v_max_f32_e32 v86, v114, v9
	v_max_f32_e32 v87, v115, v6
	ds_bpermute_b32 v9, v10, v8
	s_waitcnt lgkmcnt(1)
	v_max_f32_e32 v6, v11, v11
	ds_bpermute_b32 v11, v10, v86
	v_max_f32_e32 v6, v7, v6
	ds_bpermute_b32 v7, v10, v87
	s_waitcnt lgkmcnt(2)
	v_max_f32_e32 v9, v9, v9
	v_cmp_lt_i32_e32 vcc, v24, v21
	v_max_f32_e32 v9, v8, v9
	s_waitcnt lgkmcnt(1)
	v_max_f32_e32 v8, v11, v11
	s_waitcnt lgkmcnt(0)
	v_max_f32_e32 v7, v7, v7
	v_cndmask_b32_e32 v10, v20, v24, vcc
	v_max_f32_e32 v8, v86, v8
	v_max_f32_e32 v7, v87, v7
	v_lshlrev_b32_e32 v10, 2, v10
	ds_bpermute_b32 v87, v10, v6
	ds_bpermute_b32 v86, v10, v9
	ds_bpermute_b32 v11, v10, v8
	ds_bpermute_b32 v10, v10, v7
	s_and_saveexec_b64 s[2:3], s[4:5]
	s_cbranch_execz .LBB0_198
	s_waitcnt lgkmcnt(3)
	v_max_f32_e32 v87, v87, v87
	v_max_f32_e32 v6, v6, v6
	v_max_f32_e32 v88, v6, v87
	s_waitcnt lgkmcnt(2)
	v_max_f32_e32 v6, v86, v86
	v_max_f32_e32 v9, v9, v9
	v_max_f32_e32 v89, v9, v6
	s_waitcnt lgkmcnt(1)
	v_max_f32_e32 v6, v11, v11
	v_max_f32_e32 v8, v8, v8
	v_max_f32_e32 v90, v8, v6
	s_waitcnt lgkmcnt(0)
	v_max_f32_e32 v6, v10, v10
	v_max_f32_e32 v7, v7, v7
	v_max_f32_e32 v91, v7, v6
	ds_write_b128 v17, v[88:91]
